# p7b_quant: per-token max reduction via DPP row ops + permlane swaps instead of six ds_bpermute round trips
# baseline (speedup 1.0000x reference)
; __device__ __forceinline__ void p7b_quant(Frame& F) {
;     ...
;     for (int t0 = gw; t0 < NT_TOK; t0 += 4 * NGW) {
;         float ca[4], cb[4];
; #pragma unroll
;         for (int k = 0; k < 4; ++k) { const int t = t0 + k * NGW < NT_TOK ? t0 + k * NGW : t0; ca[k] = RG[(size_t)t * 128 + lane]; cb[k] = RG[(size_t)t * 128 + 64 + lane]; }
; #pragma unroll
;         for (int k = 0; k < 4; ++k) { const int t = t0 + k * NGW; if (t < NT_TOK) {
;             float am = fmaxf(fabsf(ca[k]), fabsf(cb[k]));
; #pragma unroll
;             for (int o = 1; o < 64; o <<= 1) am = fmaxf(am, __shfl_xor(am, o));
;             const float inv = am > 0.f ? 127.0f / am : 0.f;
;             const int qa = (int)__builtin_rintf(ca[k] * inv) & 0xff, qb = (int)__builtin_rintf(cb[k] * inv) & 0xff;
;             const int wa = qa | (__shfl_down(qa, 8) << 8) | (__shfl_down(qa, 16) << 16) | (__shfl_down(qa, 24) << 24);
;             const int wb = qb | (__shfl_down(qb, 8) << 8) | (__shfl_down(qb, 16) << 16) | (__shfl_down(qb, 24) << 24);
;             if (((lane >> 3) & 3) == 0) { unsigned* cq = CQ + (size_t)t * 32 + (lane & 7) * 4 + (lane >> 5); cq[0] = (unsigned)wa; cq[2] = (unsigned)wb; }
;             if (lane == 0) SCQ[t] = am * (1.0f / 127.0f); } }
.LBB0_1008:
	s_ashr_i32 s13, s12, 31
	s_add_i32 s2, s12, s34
	s_cmpk_lt_i32 s2, 0x6000
	s_cselect_b64 s[14:15], -1, 0
	s_and_b64 s[0:1], s[14:15], exec
	s_cselect_b32 s0, s2, s12
	s_ashr_i32 s1, s0, 31
	s_lshl_b64 s[0:1], s[0:1], 9
	s_add_i32 s6, s16, s12
	s_cmpk_lt_i32 s6, 0x6000
	s_cselect_b64 s[10:11], -1, 0
	s_waitcnt lgkmcnt(5)
	v_lshl_add_u64 v[14:15], v[4:5], 0, s[0:1]
	s_and_b64 s[0:1], s[10:11], exec
	s_cselect_b32 s0, s6, s12
	s_ashr_i32 s1, s0, 31
	s_lshl_b64 s[0:1], s[0:1], 9
	s_waitcnt lgkmcnt(3)
	global_load_dword v19, v[14:15], off
	global_load_dword v18, v[14:15], off offset:256
	v_lshl_add_u64 v[14:15], v[4:5], 0, s[0:1]
	s_mul_i32 s0, s68, 24
	s_add_i32 s4, s0, s12
	s_cmpk_lt_i32 s4, 0x6000
	s_cselect_b64 s[8:9], -1, 0
	s_and_b64 s[0:1], s[8:9], exec
	s_cselect_b32 s0, s4, s12
	s_ashr_i32 s1, s0, 31
	s_lshl_b64 s[0:1], s[0:1], 9
	s_waitcnt lgkmcnt(1)
	v_lshl_add_u64 v[20:21], v[4:5], 0, s[0:1]
	s_lshl_b64 s[0:1], s[12:13], 9
	global_load_dword v17, v[14:15], off
	global_load_dword v16, v[14:15], off offset:256
	s_nop 0
	global_load_dword v15, v[20:21], off
	global_load_dword v14, v[20:21], off offset:256
	v_lshl_add_u64 v[20:21], v[4:5], 0, s[0:1]
	s_waitcnt lgkmcnt(0)
	global_load_dword v22, v[20:21], off offset:256
	s_nop 0
	global_load_dword v21, v[20:21], off
	s_waitcnt vmcnt(1)
	v_max_f32_e64 v20, |v22|, |v22|
	s_waitcnt vmcnt(0)
	v_max_f32_e64 v23, |v21|, |v21|
	v_max_f32_e32 v20, v23, v20
	s_waitcnt lgkmcnt(0)
	s_nop 1
	v_max_f32_dpp v20, v20, v20 quad_perm:[1,0,3,2] row_mask:0xf bank_mask:0xf
	s_nop 1
	v_max_f32_dpp v20, v20, v20 quad_perm:[2,3,0,1] row_mask:0xf bank_mask:0xf
	s_nop 1
	v_max_f32_dpp v20, v20, v20 row_half_mirror row_mask:0xf bank_mask:0xf
	s_nop 1
	v_max_f32_dpp v20, v20, v20 row_mirror row_mask:0xf bank_mask:0xf
	v_mov_b32_e32 v23, v20
	s_nop 1
	v_permlane16_swap_b32_e32 v20, v23
	v_max_f32_e32 v20, v20, v23
	v_mov_b32_e32 v23, v20
	s_nop 1
	v_permlane32_swap_b32_e32 v20, v23
	v_max_f32_e32 v20, v20, v23
	v_div_scale_f32 v23, s[18:19], v20, v20, s17
	v_rcp_f32_e32 v24, v23
	v_cmp_lt_f32_e64 s[0:1], 0, v20
	v_fma_f32 v25, -v23, v24, 1.0
	v_fmac_f32_e32 v24, v25, v24
	v_div_scale_f32 v25, vcc, s17, v20, s17
	v_mul_f32_e32 v26, v25, v24
	v_fma_f32 v27, -v23, v26, v25
	v_fmac_f32_e32 v26, v27, v24
	v_fma_f32 v23, -v23, v26, v25
	v_div_fmas_f32 v23, v23, v24, v26
	v_div_fixup_f32 v23, v23, v20, s17
	v_cndmask_b32_e64 v23, 0, v23, s[0:1]
	v_mul_f32_e32 v21, v21, v23
	v_mul_f32_e32 v22, v22, v23
	v_rndne_f32_e32 v21, v21
	v_rndne_f32_e32 v22, v22
	v_cvt_i32_f32_e32 v21, v21
	v_cvt_i32_f32_e32 v22, v22
	v_and_b32_e32 v21, 0xff, v21
	v_and_b32_e32 v24, 0xff, v22
	ds_bpermute_b32 v22, v11, v21
	ds_bpermute_b32 v23, v12, v21
	ds_bpermute_b32 v25, v13, v21
	ds_bpermute_b32 v26, v11, v24
	ds_bpermute_b32 v27, v12, v24
	ds_bpermute_b32 v28, v13, v24
	s_and_saveexec_b64 s[0:1], s[36:37]
	s_cbranch_execz .LBB0_1017
	s_waitcnt lgkmcnt(5)
	v_lshlrev_b32_e32 v22, 8, v22
	s_waitcnt lgkmcnt(2)
	v_lshlrev_b32_e32 v26, 8, v26
	v_lshlrev_b32_e32 v25, 24, v25
	v_lshl_or_b32 v22, v23, 16, v22
	s_lshl_b64 s[18:19], s[12:13], 7
	s_waitcnt lgkmcnt(0)
	v_lshlrev_b32_e32 v28, 24, v28
	v_lshl_or_b32 v26, v27, 16, v26
	v_or3_b32 v21, v22, v25, v21
	v_lshl_add_u64 v[22:23], v[2:3], 0, s[18:19]
	v_or3_b32 v24, v26, v28, v24
	global_store_dword v[22:23], v21, off
	global_store_dword v[22:23], v24, off offset:8
	s_or_b64 exec, exec, s[0:1]
	s_and_saveexec_b64 s[0:1], s[38:39]
	s_cbranch_execnz .LBB0_1018

; __device__ __forceinline__ void p7b_quant(Frame& F) {
;     ...
;         for (int k = 0; k < 4; ++k) { const int t = t0 + k * NGW; if (t < NT_TOK) {
;             float am = fmaxf(fabsf(ca[k]), fabsf(cb[k]));
; #pragma unroll
;             for (int o = 1; o < 64; o <<= 1) am = fmaxf(am, __shfl_xor(am, o));
;             const float inv = am > 0.f ? 127.0f / am : 0.f;
;             const int qa = (int)__builtin_rintf(ca[k] * inv) & 0xff, qb = (int)__builtin_rintf(cb[k] * inv) & 0xff;
;             const int wa = qa | (__shfl_down(qa, 8) << 8) | (__shfl_down(qa, 16) << 16) | (__shfl_down(qa, 24) << 24);
;             const int wb = qb | (__shfl_down(qb, 8) << 8) | (__shfl_down(qb, 16) << 16) | (__shfl_down(qb, 24) << 24);
;             if (((lane >> 3) & 3) == 0) { unsigned* cq = CQ + (size_t)t * 32 + (lane & 7) * 4 + (lane >> 5); cq[0] = (unsigned)wa; cq[2] = (unsigned)wb; }
;             if (lane == 0) SCQ[t] = am * (1.0f / 127.0f); } }
.LBB0_1011:
	v_max_f32_e64 v20, |v18|, |v18|
	v_max_f32_e64 v21, |v19|, |v19|
	v_max_f32_e32 v20, v21, v20
	s_waitcnt lgkmcnt(0)
	s_nop 1
	v_max_f32_dpp v20, v20, v20 quad_perm:[1,0,3,2] row_mask:0xf bank_mask:0xf
	s_nop 1
	v_max_f32_dpp v20, v20, v20 quad_perm:[2,3,0,1] row_mask:0xf bank_mask:0xf
	s_nop 1
	v_max_f32_dpp v20, v20, v20 row_half_mirror row_mask:0xf bank_mask:0xf
	s_nop 1
	v_max_f32_dpp v20, v20, v20 row_mirror row_mask:0xf bank_mask:0xf
	v_mov_b32_e32 v21, v20
	s_nop 1
	v_permlane16_swap_b32_e32 v20, v21
	v_max_f32_e32 v20, v20, v21
	v_mov_b32_e32 v21, v20
	s_nop 1
	v_permlane32_swap_b32_e32 v20, v21
	v_max_f32_e32 v20, v20, v21
	v_div_scale_f32 v21, s[0:1], v20, v20, s17
	v_rcp_f32_e32 v22, v21
	v_div_scale_f32 v23, vcc, s17, v20, s17
	v_fma_f32 v24, -v21, v22, 1.0
	v_fmac_f32_e32 v22, v24, v22
	v_mul_f32_e32 v24, v23, v22
	v_fma_f32 v25, -v21, v24, v23
	v_fmac_f32_e32 v24, v25, v22
	v_fma_f32 v21, -v21, v24, v23
	v_div_fmas_f32 v21, v21, v22, v24
	v_div_fixup_f32 v21, v21, v20, s17
	v_cmp_lt_f32_e32 vcc, 0, v20
	s_nop 1
	v_cndmask_b32_e32 v21, 0, v21, vcc
	v_mul_f32_e32 v19, v19, v21
	v_mul_f32_e32 v18, v18, v21
	v_rndne_f32_e32 v19, v19
	v_rndne_f32_e32 v18, v18
	v_cvt_i32_f32_e32 v19, v19
	v_cvt_i32_f32_e32 v21, v18
	v_and_b32_e32 v18, 0xff, v19
	v_and_b32_e32 v22, 0xff, v21
	ds_bpermute_b32 v19, v11, v18
	ds_bpermute_b32 v21, v12, v18
	ds_bpermute_b32 v23, v13, v18
	ds_bpermute_b32 v24, v11, v22
	ds_bpermute_b32 v25, v12, v22
	ds_bpermute_b32 v26, v13, v22
	s_and_saveexec_b64 s[0:1], s[36:37]
	s_cbranch_execz .LBB0_1013
	s_waitcnt lgkmcnt(5)
	v_lshlrev_b32_e32 v19, 8, v19
	s_ashr_i32 s3, s2, 31
	s_waitcnt lgkmcnt(2)
	v_lshlrev_b32_e32 v24, 8, v24
	v_lshlrev_b32_e32 v23, 24, v23
	v_lshl_or_b32 v19, v21, 16, v19
	s_lshl_b64 s[12:13], s[2:3], 7
	s_waitcnt lgkmcnt(0)
	v_lshlrev_b32_e32 v26, 24, v26
	v_lshl_or_b32 v24, v25, 16, v24
	v_or3_b32 v21, v19, v23, v18
	v_lshl_add_u64 v[18:19], v[2:3], 0, s[12:13]
	v_or3_b32 v22, v24, v26, v22
	global_store_dword v[18:19], v21, off
	global_store_dword v[18:19], v22, off offset:8

; __device__ __forceinline__ void p7b_quant(Frame& F) {
;     ...
;         for (int k = 0; k < 4; ++k) { const int t = t0 + k * NGW; if (t < NT_TOK) {
;             float am = fmaxf(fabsf(ca[k]), fabsf(cb[k]));
; #pragma unroll
;             for (int o = 1; o < 64; o <<= 1) am = fmaxf(am, __shfl_xor(am, o));
;             const float inv = am > 0.f ? 127.0f / am : 0.f;
;             const int qa = (int)__builtin_rintf(ca[k] * inv) & 0xff, qb = (int)__builtin_rintf(cb[k] * inv) & 0xff;
;             const int wa = qa | (__shfl_down(qa, 8) << 8) | (__shfl_down(qa, 16) << 16) | (__shfl_down(qa, 24) << 24);
;             const int wb = qb | (__shfl_down(qb, 8) << 8) | (__shfl_down(qb, 16) << 16) | (__shfl_down(qb, 24) << 24);
;             if (((lane >> 3) & 3) == 0) { unsigned* cq = CQ + (size_t)t * 32 + (lane & 7) * 4 + (lane >> 5); cq[0] = (unsigned)wa; cq[2] = (unsigned)wb; }
;             if (lane == 0) SCQ[t] = am * (1.0f / 127.0f); } }
.LBB0_1020:
	v_max_f32_e64 v18, |v16|, |v16|
	s_waitcnt lgkmcnt(5)
	v_max_f32_e64 v19, |v17|, |v17|
	v_max_f32_e32 v18, v19, v18
	s_waitcnt lgkmcnt(0)
	s_nop 1
	v_max_f32_dpp v18, v18, v18 quad_perm:[1,0,3,2] row_mask:0xf bank_mask:0xf
	s_nop 1
	v_max_f32_dpp v18, v18, v18 quad_perm:[2,3,0,1] row_mask:0xf bank_mask:0xf
	s_nop 1
	v_max_f32_dpp v18, v18, v18 row_half_mirror row_mask:0xf bank_mask:0xf
	s_nop 1
	v_max_f32_dpp v18, v18, v18 row_mirror row_mask:0xf bank_mask:0xf
	v_mov_b32_e32 v19, v18
	s_nop 1
	v_permlane16_swap_b32_e32 v18, v19
	v_max_f32_e32 v18, v18, v19
	v_mov_b32_e32 v19, v18
	s_nop 1
	v_permlane32_swap_b32_e32 v18, v19
	v_max_f32_e32 v18, v18, v19
	v_div_scale_f32 v19, s[0:1], v18, v18, s17
	v_rcp_f32_e32 v20, v19
	v_div_scale_f32 v21, vcc, s17, v18, s17
	v_fma_f32 v22, -v19, v20, 1.0
	v_fmac_f32_e32 v20, v22, v20
	v_mul_f32_e32 v22, v21, v20
	v_fma_f32 v23, -v19, v22, v21
	v_fmac_f32_e32 v22, v23, v20
	v_fma_f32 v19, -v19, v22, v21
	v_div_fmas_f32 v19, v19, v20, v22
	v_div_fixup_f32 v19, v19, v18, s17
	v_cmp_lt_f32_e32 vcc, 0, v18
	s_nop 1
	v_cndmask_b32_e32 v19, 0, v19, vcc
	v_mul_f32_e32 v17, v17, v19
	v_mul_f32_e32 v16, v16, v19
	v_rndne_f32_e32 v17, v17
	v_rndne_f32_e32 v16, v16
	v_cvt_i32_f32_e32 v17, v17
	v_cvt_i32_f32_e32 v19, v16
	v_and_b32_e32 v16, 0xff, v17
	v_and_b32_e32 v20, 0xff, v19
	ds_bpermute_b32 v17, v11, v16
	ds_bpermute_b32 v19, v12, v16
	ds_bpermute_b32 v21, v13, v16
	ds_bpermute_b32 v22, v11, v20
	ds_bpermute_b32 v23, v12, v20
	ds_bpermute_b32 v24, v13, v20
	s_and_saveexec_b64 s[0:1], s[36:37]
	s_cbranch_execz .LBB0_1022
	s_waitcnt lgkmcnt(5)
	v_lshlrev_b32_e32 v17, 8, v17
	s_ashr_i32 s7, s6, 31
	s_waitcnt lgkmcnt(2)
	v_lshlrev_b32_e32 v22, 8, v22
	v_lshlrev_b32_e32 v21, 24, v21
	v_lshl_or_b32 v17, v19, 16, v17
	s_lshl_b64 s[10:11], s[6:7], 7
	s_waitcnt lgkmcnt(0)
	v_lshlrev_b32_e32 v24, 24, v24
	v_lshl_or_b32 v22, v23, 16, v22
	v_or3_b32 v19, v17, v21, v16
	v_lshl_add_u64 v[16:17], v[2:3], 0, s[10:11]
	v_or3_b32 v20, v22, v24, v20
	global_store_dword v[16:17], v19, off
	global_store_dword v[16:17], v20, off offset:8

; __device__ __forceinline__ void p7b_quant(Frame& F) {
;     ...
;         for (int k = 0; k < 4; ++k) { const int t = t0 + k * NGW; if (t < NT_TOK) {
;             float am = fmaxf(fabsf(ca[k]), fabsf(cb[k]));
; #pragma unroll
;             for (int o = 1; o < 64; o <<= 1) am = fmaxf(am, __shfl_xor(am, o));
;             const float inv = am > 0.f ? 127.0f / am : 0.f;
;             const int qa = (int)__builtin_rintf(ca[k] * inv) & 0xff, qb = (int)__builtin_rintf(cb[k] * inv) & 0xff;
;             const int wa = qa | (__shfl_down(qa, 8) << 8) | (__shfl_down(qa, 16) << 16) | (__shfl_down(qa, 24) << 24);
;             const int wb = qb | (__shfl_down(qb, 8) << 8) | (__shfl_down(qb, 16) << 16) | (__shfl_down(qb, 24) << 24);
;             if (((lane >> 3) & 3) == 0) { unsigned* cq = CQ + (size_t)t * 32 + (lane & 7) * 4 + (lane >> 5); cq[0] = (unsigned)wa; cq[2] = (unsigned)wb; }
;             if (lane == 0) SCQ[t] = am * (1.0f / 127.0f); } }
.LBB0_1025:
	v_max_f32_e64 v16, |v14|, |v14|
	s_waitcnt lgkmcnt(5)
	v_max_f32_e64 v17, |v15|, |v15|
	v_max_f32_e32 v16, v17, v16
	s_waitcnt lgkmcnt(0)
	s_nop 1
	v_max_f32_dpp v16, v16, v16 quad_perm:[1,0,3,2] row_mask:0xf bank_mask:0xf
	s_nop 1
	v_max_f32_dpp v16, v16, v16 quad_perm:[2,3,0,1] row_mask:0xf bank_mask:0xf
	s_nop 1
	v_max_f32_dpp v16, v16, v16 row_half_mirror row_mask:0xf bank_mask:0xf
	s_nop 1
	v_max_f32_dpp v16, v16, v16 row_mirror row_mask:0xf bank_mask:0xf
	v_mov_b32_e32 v17, v16
	s_nop 1
	v_permlane16_swap_b32_e32 v16, v17
	v_max_f32_e32 v16, v16, v17
	v_mov_b32_e32 v17, v16
	s_nop 1
	v_permlane32_swap_b32_e32 v16, v17
	v_max_f32_e32 v16, v16, v17
	v_div_scale_f32 v17, s[0:1], v16, v16, s17
	v_rcp_f32_e32 v18, v17
	v_div_scale_f32 v19, vcc, s17, v16, s17
	v_fma_f32 v20, -v17, v18, 1.0
	v_fmac_f32_e32 v18, v20, v18
	v_mul_f32_e32 v20, v19, v18
	v_fma_f32 v21, -v17, v20, v19
	v_fmac_f32_e32 v20, v21, v18
	v_fma_f32 v17, -v17, v20, v19
	v_div_fmas_f32 v17, v17, v18, v20
	v_div_fixup_f32 v17, v17, v16, s17
	v_cmp_lt_f32_e32 vcc, 0, v16
	s_nop 1
	v_cndmask_b32_e32 v17, 0, v17, vcc
	v_mul_f32_e32 v15, v15, v17
	v_mul_f32_e32 v14, v14, v17
	v_rndne_f32_e32 v15, v15
	v_rndne_f32_e32 v14, v14
	v_cvt_i32_f32_e32 v15, v15
	v_cvt_i32_f32_e32 v17, v14
	v_and_b32_e32 v14, 0xff, v15
	v_and_b32_e32 v18, 0xff, v17
	ds_bpermute_b32 v15, v11, v14
	ds_bpermute_b32 v17, v12, v14
	ds_bpermute_b32 v19, v13, v14
	ds_bpermute_b32 v20, v11, v18
	ds_bpermute_b32 v21, v12, v18
	ds_bpermute_b32 v22, v13, v18
	s_and_saveexec_b64 s[0:1], s[36:37]
	s_cbranch_execz .LBB0_1027
	s_waitcnt lgkmcnt(5)
	v_lshlrev_b32_e32 v15, 8, v15
	s_ashr_i32 s5, s4, 31
	s_waitcnt lgkmcnt(2)
	v_lshlrev_b32_e32 v20, 8, v20
	v_lshlrev_b32_e32 v19, 24, v19
	v_lshl_or_b32 v15, v17, 16, v15
	s_lshl_b64 s[6:7], s[4:5], 7
	s_waitcnt lgkmcnt(0)
	v_lshlrev_b32_e32 v22, 24, v22
	v_lshl_or_b32 v20, v21, 16, v20
	v_or3_b32 v17, v15, v19, v14
	v_lshl_add_u64 v[14:15], v[2:3], 0, s[6:7]
	v_or3_b32 v18, v20, v22, v18
	global_store_dword v[14:15], v17, off
	global_store_dword v[14:15], v18, off offset:8
